# GLA scan chunk compute hand-scheduled: LDS fragment reads issued up to 15 ahead of their MFMAs (counted lgkmcnt), K^T second block in spare VGPRs
# speedup vs baseline: 1.0412x; 1.0065x over previous
.LBB0_515:
	s_waitcnt lgkmcnt(0)
	v_add_u32_e32 v154, 0x1000, v134
	v_add_u32_e32 v143, v111, v145
	ds_read_b64_tr_b16 v[156:157], v135
	ds_read_b64_tr_b16 v[158:159], v135 offset:576
	ds_read_b64_tr_b16 v[92:93], v135 offset:4608
	ds_read_b64_tr_b16 v[94:95], v135 offset:5184
	ds_read_b128 v[96:99], v141 offset:44032
	ds_read_b128 v[200:203], v141 offset:44096
	ds_read_b128 v[100:103], v141 offset:46336
	ds_read_b128 v[204:207], v141 offset:46400
	ds_read2_b64 v[160:163], v134 offset0:0 offset1:4
	ds_read2_b64 v[164:167], v154 offset0:32 offset1:36
	ds_read2_b64 v[208:211], v134 offset0:8 offset1:12
	ds_read2_b64 v[212:215], v154 offset0:40 offset1:44
	ds_read2_b64 v[216:219], v134 offset0:16 offset1:20
	ds_read2_b64 v[220:223], v154 offset0:48 offset1:52
	ds_read2_b64 v[224:227], v134 offset0:24 offset1:28
	ds_read2_b64 v[228:231], v154 offset0:56 offset1:60
	ds_read_b64_tr_b16 v[196:197], v129 offset:0
	ds_read_b64_tr_b16 v[198:199], v129 offset:1088
	ds_read_b64_tr_b16 v[192:193], v129 offset:32
	ds_read_b64_tr_b16 v[194:195], v129 offset:1120
	s_waitcnt lgkmcnt(15)
	v_mfma_f32_16x16x32_bf16 v[96:99], v[156:159], v[96:99], 0
	ds_read_b64_tr_b16 v[188:189], v129 offset:64
	s_waitcnt lgkmcnt(15)
	v_mfma_f32_16x16x32_bf16 v[96:99], v[92:95], v[200:203], v[96:99]
	ds_read_b64_tr_b16 v[190:191], v129 offset:1152
	s_waitcnt lgkmcnt(15)
	v_mfma_f32_16x16x32_bf16 v[100:103], v[156:159], v[100:103], 0
	ds_read_b64_tr_b16 v[184:185], v129 offset:96
	s_waitcnt lgkmcnt(15)
	v_mfma_f32_16x16x32_bf16 v[100:103], v[92:95], v[204:207], v[100:103]
	v_cvt_pk_bf16_f32 v104, v0, v1
	v_cvt_pk_bf16_f32 v105, v2, v3
	v_cvt_pk_bf16_f32 v106, v4, v5
	v_cvt_pk_bf16_f32 v107, v6, v7
	ds_read_b64_tr_b16 v[186:187], v129 offset:1184
	s_nop 1
	s_waitcnt lgkmcnt(15)
	v_mfma_f32_16x16x32_bf16 v[96:99], v[104:107], v[160:163], v[96:99]
	ds_read_b64_tr_b16 v[180:181], v129 offset:128
	s_waitcnt lgkmcnt(15)
	v_mfma_f32_16x16x32_bf16 v[100:103], v[104:107], v[164:167], v[100:103]
	v_cvt_pk_bf16_f32 v104, v8, v9
	v_cvt_pk_bf16_f32 v105, v10, v11
	v_cvt_pk_bf16_f32 v106, v12, v13
	v_cvt_pk_bf16_f32 v107, v14, v15
	ds_read_b64_tr_b16 v[182:183], v129 offset:1216
	s_nop 1
	s_waitcnt lgkmcnt(15)
	v_mfma_f32_16x16x32_bf16 v[96:99], v[104:107], v[208:211], v[96:99]
	ds_read_b64_tr_b16 v[176:177], v129 offset:160
	s_waitcnt lgkmcnt(15)
	v_mfma_f32_16x16x32_bf16 v[100:103], v[104:107], v[212:215], v[100:103]
	v_cvt_pk_bf16_f32 v104, v16, v17
	v_cvt_pk_bf16_f32 v105, v18, v19
	v_cvt_pk_bf16_f32 v106, v20, v21
	v_cvt_pk_bf16_f32 v107, v22, v23
	ds_read_b64_tr_b16 v[178:179], v129 offset:1248
	s_nop 1
	s_waitcnt lgkmcnt(15)
	v_mfma_f32_16x16x32_bf16 v[96:99], v[104:107], v[216:219], v[96:99]
	ds_read_b64_tr_b16 v[172:173], v129 offset:192
	s_waitcnt lgkmcnt(15)
	v_mfma_f32_16x16x32_bf16 v[100:103], v[104:107], v[220:223], v[100:103]
	v_cvt_pk_bf16_f32 v104, v24, v25
	v_cvt_pk_bf16_f32 v105, v26, v27
	v_cvt_pk_bf16_f32 v106, v28, v29
	v_cvt_pk_bf16_f32 v107, v30, v31
	ds_read_b64_tr_b16 v[174:175], v129 offset:1280
	s_nop 1
	s_waitcnt lgkmcnt(15)
	v_mfma_f32_16x16x32_bf16 v[96:99], v[104:107], v[224:227], v[96:99]
	ds_read_b64_tr_b16 v[168:169], v129 offset:224
	ds_read_b64_tr_b16 v[170:171], v129 offset:1312
	ds_read_b64_tr_b16 v[232:233], v130 offset:0
	s_waitcnt lgkmcnt(15)
	v_mfma_f32_16x16x32_bf16 v[0:3], v[196:199], v[156:159], v[0:3]
	ds_read_b64_tr_b16 v[234:235], v130 offset:1088
	ds_read_b64_tr_b16 v[236:237], v130 offset:32
	s_waitcnt lgkmcnt(15)
	v_mfma_f32_16x16x32_bf16 v[4:7], v[192:195], v[156:159], v[4:7]
	ds_read_b64_tr_b16 v[238:239], v130 offset:1120
	ds_read_b64_tr_b16 v[240:241], v130 offset:64
	s_waitcnt lgkmcnt(15)
	v_mfma_f32_16x16x32_bf16 v[8:11], v[188:191], v[156:159], v[8:11]
	ds_read_b64_tr_b16 v[242:243], v130 offset:1152
	ds_read_b64_tr_b16 v[244:245], v130 offset:96
	s_waitcnt lgkmcnt(15)
	v_mfma_f32_16x16x32_bf16 v[12:15], v[184:187], v[156:159], v[12:15]
	ds_read_b64_tr_b16 v[246:247], v130 offset:1184
	ds_read_b64_tr_b16 v[200:201], v130 offset:128
	s_waitcnt lgkmcnt(15)
	v_mfma_f32_16x16x32_bf16 v[16:19], v[180:183], v[156:159], v[16:19]
	ds_read_b64_tr_b16 v[202:203], v130 offset:1216
	ds_read_b64_tr_b16 v[204:205], v130 offset:160
	s_waitcnt lgkmcnt(15)
	v_mfma_f32_16x16x32_bf16 v[20:23], v[176:179], v[156:159], v[20:23]
	ds_read_b64_tr_b16 v[206:207], v130 offset:1248
	ds_read_b64_tr_b16 v[160:161], v130 offset:192
	s_waitcnt lgkmcnt(15)
	v_mfma_f32_16x16x32_bf16 v[24:27], v[172:175], v[156:159], v[24:27]
	ds_read_b64_tr_b16 v[162:163], v130 offset:1280
	ds_read_b64_tr_b16 v[164:165], v130 offset:224
	s_waitcnt lgkmcnt(15)
	v_mfma_f32_16x16x32_bf16 v[28:31], v[168:171], v[156:159], v[28:31]
	ds_read_b64_tr_b16 v[166:167], v130 offset:1312
	ds_read_b128 v[196:199], v143 offset:53248
	s_waitcnt lgkmcnt(15)
	v_mfma_f32_16x16x32_bf16 v[0:3], v[232:235], v[92:95], v[0:3]
	ds_read_b128 v[192:195], v143 offset:53312
	ds_read_b128 v[188:191], v143 offset:53376
	s_waitcnt lgkmcnt(15)
	v_mfma_f32_16x16x32_bf16 v[4:7], v[236:239], v[92:95], v[4:7]
	ds_read_b128 v[184:187], v143 offset:53440
	ds_read_b128 v[180:183], v143 offset:53504
	s_waitcnt lgkmcnt(15)
	v_mfma_f32_16x16x32_bf16 v[8:11], v[240:243], v[92:95], v[8:11]
	ds_read_b128 v[176:179], v143 offset:53568
	ds_read_b128 v[172:175], v143 offset:53632
	s_waitcnt lgkmcnt(15)
	v_mfma_f32_16x16x32_bf16 v[12:15], v[244:247], v[92:95], v[12:15]
	ds_read_b128 v[168:171], v143 offset:53696
	s_waitcnt lgkmcnt(14)
	v_mfma_f32_16x16x32_bf16 v[16:19], v[200:203], v[92:95], v[16:19]
	s_waitcnt lgkmcnt(12)
	v_mfma_f32_16x16x32_bf16 v[20:23], v[204:207], v[92:95], v[20:23]
	s_waitcnt lgkmcnt(10)
	v_mfma_f32_16x16x32_bf16 v[24:27], v[160:163], v[92:95], v[24:27]
	s_waitcnt lgkmcnt(8)
	v_mfma_f32_16x16x32_bf16 v[28:31], v[164:167], v[92:95], v[28:31]
	v_mfma_f32_16x16x32_bf16 v[92:95], v[104:107], v[228:231], v[100:103]
	s_waitcnt lgkmcnt(0)
	s_barrier
	v_pk_mul_f32 v[2:3], v[2:3], v[198:199]
	v_pk_mul_f32 v[0:1], v[0:1], v[196:197]
	v_pk_mul_f32 v[6:7], v[6:7], v[194:195]
	v_pk_mul_f32 v[4:5], v[4:5], v[192:193]
	v_pk_mul_f32 v[10:11], v[10:11], v[190:191]
	v_pk_mul_f32 v[8:9], v[8:9], v[188:189]
	v_pk_mul_f32 v[14:15], v[14:15], v[186:187]
	v_pk_mul_f32 v[12:13], v[12:13], v[184:185]
	v_pk_mul_f32 v[18:19], v[18:19], v[182:183]
	v_pk_mul_f32 v[16:17], v[16:17], v[180:181]
	v_pk_mul_f32 v[22:23], v[22:23], v[178:179]
	v_pk_mul_f32 v[20:21], v[20:21], v[176:177]
	v_pk_mul_f32 v[26:27], v[26:27], v[174:175]
	v_pk_mul_f32 v[24:25], v[24:25], v[172:173]
	v_pk_mul_f32 v[30:31], v[30:31], v[170:171]
	v_pk_mul_f32 v[28:29], v[28:29], v[168:169]
	s_add_i32 s0, s35, -2
	s_cmp_ge_u32 s0, s31
	s_cbranch_scc1 .LBB0_527
	ds_write_b128 v139, v[68:71]
	ds_write_b128 v140, v[72:75]
	ds_write_b128 v139, v[76:79] offset:17408
	ds_write_b128 v140, v[80:83] offset:17408
	ds_write_b128 v138, v[84:87] offset:44032
	ds_write_b128 v138, v[88:91] offset:34816
	s_and_saveexec_b64 s[22:23], s[8:9]
	v_add_u32_e32 v52, 0, v144
	ds_write_b128 v52, v[64:67] offset:53248
	s_or_b64 exec, exec, s[22:23]
	v_and_b32_e32 v55, 64, v151
	v_mul_f32_e32 v52, v97, v97
	v_xor_b32_e32 v54, 16, v151
	v_add_u32_e32 v101, 64, v55
	v_fmac_f32_e32 v52, v96, v96
	v_cmp_lt_i32_e32 vcc, v54, v101
	v_fmac_f32_e32 v52, v98, v98
	v_fmac_f32_e32 v52, v99, v99
	v_cndmask_b32_e32 v54, v151, v54, vcc
	v_lshlrev_b32_e32 v100, 2, v54
	ds_bpermute_b32 v54, v100, v52
	s_waitcnt lgkmcnt(0)
	s_barrier
	v_cvt_pk_bf16_f32 v102, v96, v97
	s_waitcnt lgkmcnt(0)
	v_add_f32_e32 v55, v52, v54
	v_xor_b32_e32 v52, 32, v151
	v_cmp_lt_i32_e32 vcc, v52, v101
	v_cvt_pk_bf16_f32 v103, v98, v99
	v_add_u32_e32 v54, s48, v148
	s_nop 0
	v_cndmask_b32_e32 v52, v151, v52, vcc
	v_lshlrev_b32_e32 v96, 2, v52
	ds_bpermute_b32 v97, v96, v55
	v_add_u32_e32 v52, s37, v149
	v_lshl_add_u64 v[98:99], v[52:53], 1, v[120:121]
	global_store_dwordx2 v[98:99], v[102:103], off
	s_and_saveexec_b64 s[22:23], s[4:5]
	s_cbranch_execz .LBB0_520
	s_waitcnt lgkmcnt(0)
	v_add_f32_e32 v97, v55, v97
	v_mov_b32_e32 v55, v53
	v_lshl_add_u64 v[98:99], v[54:55], 2, s[42:43]
	global_store_dword v[98:99], v97, off

.LBB0_526:
	s_waitcnt lgkmcnt(0)
	s_mov_b32 s0, s36
	ds_read_b64_tr_b16 v[156:157], v135
	ds_read_b64_tr_b16 v[158:159], v135 offset:576
	ds_read_b64_tr_b16 v[92:93], v135 offset:4608
	ds_read_b64_tr_b16 v[94:95], v135 offset:5184
	ds_read_b128 v[96:99], v141 offset:44032
	ds_read_b128 v[200:203], v141 offset:44096
	ds_read_b128 v[100:103], v141 offset:46336
	ds_read_b128 v[204:207], v141 offset:46400
	ds_read2_b64 v[160:163], v134 offset0:0 offset1:4
	ds_read2_b64 v[164:167], v154 offset0:32 offset1:36
	ds_read2_b64 v[208:211], v134 offset0:8 offset1:12
	ds_read2_b64 v[212:215], v154 offset0:40 offset1:44
	ds_read2_b64 v[216:219], v134 offset0:16 offset1:20
	ds_read2_b64 v[220:223], v154 offset0:48 offset1:52
	ds_read2_b64 v[224:227], v134 offset0:24 offset1:28
	ds_read2_b64 v[228:231], v154 offset0:56 offset1:60
	ds_read_b64_tr_b16 v[196:197], v129 offset:0
	ds_read_b64_tr_b16 v[198:199], v129 offset:1088
	ds_read_b64_tr_b16 v[192:193], v129 offset:32
	ds_read_b64_tr_b16 v[194:195], v129 offset:1120
	s_waitcnt lgkmcnt(15)
	v_mfma_f32_16x16x32_bf16 v[96:99], v[156:159], v[96:99], 0
	ds_read_b64_tr_b16 v[188:189], v129 offset:64
	s_waitcnt lgkmcnt(15)
	v_mfma_f32_16x16x32_bf16 v[96:99], v[92:95], v[200:203], v[96:99]
	ds_read_b64_tr_b16 v[190:191], v129 offset:1152
	s_waitcnt lgkmcnt(15)
	v_mfma_f32_16x16x32_bf16 v[100:103], v[156:159], v[100:103], 0
	ds_read_b64_tr_b16 v[184:185], v129 offset:96
	s_waitcnt lgkmcnt(15)
	v_mfma_f32_16x16x32_bf16 v[100:103], v[92:95], v[204:207], v[100:103]
	v_cvt_pk_bf16_f32 v104, v0, v1
	v_cvt_pk_bf16_f32 v105, v2, v3
	v_cvt_pk_bf16_f32 v106, v4, v5
	v_cvt_pk_bf16_f32 v107, v6, v7
	ds_read_b64_tr_b16 v[186:187], v129 offset:1184
	s_nop 1
	s_waitcnt lgkmcnt(15)
	v_mfma_f32_16x16x32_bf16 v[96:99], v[104:107], v[160:163], v[96:99]
	ds_read_b64_tr_b16 v[180:181], v129 offset:128
	s_waitcnt lgkmcnt(15)
	v_mfma_f32_16x16x32_bf16 v[100:103], v[104:107], v[164:167], v[100:103]
	v_cvt_pk_bf16_f32 v104, v8, v9
	v_cvt_pk_bf16_f32 v105, v10, v11
	v_cvt_pk_bf16_f32 v106, v12, v13
	v_cvt_pk_bf16_f32 v107, v14, v15
	ds_read_b64_tr_b16 v[182:183], v129 offset:1216
	s_nop 1
	s_waitcnt lgkmcnt(15)
	v_mfma_f32_16x16x32_bf16 v[96:99], v[104:107], v[208:211], v[96:99]
	ds_read_b64_tr_b16 v[176:177], v129 offset:160
	s_waitcnt lgkmcnt(15)
	v_mfma_f32_16x16x32_bf16 v[100:103], v[104:107], v[212:215], v[100:103]
	v_cvt_pk_bf16_f32 v104, v16, v17
	v_cvt_pk_bf16_f32 v105, v18, v19
	v_cvt_pk_bf16_f32 v106, v20, v21
	v_cvt_pk_bf16_f32 v107, v22, v23
	ds_read_b64_tr_b16 v[178:179], v129 offset:1248
	s_nop 1
	s_waitcnt lgkmcnt(15)
	v_mfma_f32_16x16x32_bf16 v[96:99], v[104:107], v[216:219], v[96:99]
	ds_read_b64_tr_b16 v[172:173], v129 offset:192
	s_waitcnt lgkmcnt(15)
	v_mfma_f32_16x16x32_bf16 v[100:103], v[104:107], v[220:223], v[100:103]
	v_cvt_pk_bf16_f32 v104, v24, v25
	v_cvt_pk_bf16_f32 v105, v26, v27
	v_cvt_pk_bf16_f32 v106, v28, v29
	v_cvt_pk_bf16_f32 v107, v30, v31
	ds_read_b64_tr_b16 v[174:175], v129 offset:1280
	s_nop 1
	s_waitcnt lgkmcnt(15)
	v_mfma_f32_16x16x32_bf16 v[96:99], v[104:107], v[224:227], v[96:99]
	ds_read_b64_tr_b16 v[168:169], v129 offset:224
	ds_read_b64_tr_b16 v[170:171], v129 offset:1312
	ds_read_b64_tr_b16 v[232:233], v130 offset:0
	s_waitcnt lgkmcnt(15)
	v_mfma_f32_16x16x32_bf16 v[0:3], v[196:199], v[156:159], v[0:3]
	ds_read_b64_tr_b16 v[234:235], v130 offset:1088
	ds_read_b64_tr_b16 v[236:237], v130 offset:32
	s_waitcnt lgkmcnt(15)
	v_mfma_f32_16x16x32_bf16 v[4:7], v[192:195], v[156:159], v[4:7]
	ds_read_b64_tr_b16 v[238:239], v130 offset:1120
	ds_read_b64_tr_b16 v[240:241], v130 offset:64
	s_waitcnt lgkmcnt(15)
	v_mfma_f32_16x16x32_bf16 v[8:11], v[188:191], v[156:159], v[8:11]
	ds_read_b64_tr_b16 v[242:243], v130 offset:1152
	ds_read_b64_tr_b16 v[244:245], v130 offset:96
	s_waitcnt lgkmcnt(15)
	v_mfma_f32_16x16x32_bf16 v[12:15], v[184:187], v[156:159], v[12:15]
	ds_read_b64_tr_b16 v[246:247], v130 offset:1184
	ds_read_b64_tr_b16 v[200:201], v130 offset:128
	s_waitcnt lgkmcnt(15)
	v_mfma_f32_16x16x32_bf16 v[16:19], v[180:183], v[156:159], v[16:19]
	ds_read_b64_tr_b16 v[202:203], v130 offset:1216
	ds_read_b64_tr_b16 v[204:205], v130 offset:160
	s_waitcnt lgkmcnt(15)
	v_mfma_f32_16x16x32_bf16 v[20:23], v[176:179], v[156:159], v[20:23]
	ds_read_b64_tr_b16 v[206:207], v130 offset:1248
	ds_read_b64_tr_b16 v[160:161], v130 offset:192
	s_waitcnt lgkmcnt(15)
	v_mfma_f32_16x16x32_bf16 v[24:27], v[172:175], v[156:159], v[24:27]
	ds_read_b64_tr_b16 v[162:163], v130 offset:1280
	ds_read_b64_tr_b16 v[164:165], v130 offset:224
	s_waitcnt lgkmcnt(15)
	v_mfma_f32_16x16x32_bf16 v[28:31], v[168:171], v[156:159], v[28:31]
	ds_read_b64_tr_b16 v[166:167], v130 offset:1312
	ds_read_b128 v[196:199], v143 offset:53248
	s_waitcnt lgkmcnt(15)
	v_mfma_f32_16x16x32_bf16 v[0:3], v[232:235], v[92:95], v[0:3]
	ds_read_b128 v[192:195], v143 offset:53312
	ds_read_b128 v[188:191], v143 offset:53376
	s_waitcnt lgkmcnt(15)
	v_mfma_f32_16x16x32_bf16 v[4:7], v[236:239], v[92:95], v[4:7]
	ds_read_b128 v[184:187], v143 offset:53440
	ds_read_b128 v[180:183], v143 offset:53504
	s_waitcnt lgkmcnt(15)
	v_mfma_f32_16x16x32_bf16 v[8:11], v[240:243], v[92:95], v[8:11]
	ds_read_b128 v[176:179], v143 offset:53568
	ds_read_b128 v[172:175], v143 offset:53632
	s_waitcnt lgkmcnt(15)
	v_mfma_f32_16x16x32_bf16 v[12:15], v[244:247], v[92:95], v[12:15]
	ds_read_b128 v[168:171], v143 offset:53696
	s_waitcnt lgkmcnt(14)
	v_mfma_f32_16x16x32_bf16 v[16:19], v[200:203], v[92:95], v[16:19]
	s_waitcnt lgkmcnt(12)
	v_mfma_f32_16x16x32_bf16 v[20:23], v[204:207], v[92:95], v[20:23]
	s_waitcnt lgkmcnt(10)
	v_mfma_f32_16x16x32_bf16 v[24:27], v[160:163], v[92:95], v[24:27]
	s_waitcnt lgkmcnt(8)
	v_mfma_f32_16x16x32_bf16 v[28:31], v[164:167], v[92:95], v[28:31]
	v_mfma_f32_16x16x32_bf16 v[92:95], v[104:107], v[228:231], v[100:103]
	s_waitcnt lgkmcnt(0)
	s_barrier
	v_pk_mul_f32 v[2:3], v[2:3], v[198:199]
	v_pk_mul_f32 v[0:1], v[0:1], v[196:197]
	v_pk_mul_f32 v[6:7], v[6:7], v[194:195]
	v_pk_mul_f32 v[4:5], v[4:5], v[192:193]
	v_pk_mul_f32 v[10:11], v[10:11], v[190:191]
	v_pk_mul_f32 v[8:9], v[8:9], v[188:189]
	v_pk_mul_f32 v[14:15], v[14:15], v[186:187]
	v_pk_mul_f32 v[12:13], v[12:13], v[184:185]
	v_pk_mul_f32 v[18:19], v[18:19], v[182:183]
	v_pk_mul_f32 v[16:17], v[16:17], v[180:181]
	v_pk_mul_f32 v[22:23], v[22:23], v[178:179]
	v_pk_mul_f32 v[20:21], v[20:21], v[176:177]
	v_pk_mul_f32 v[26:27], v[26:27], v[174:175]
	v_pk_mul_f32 v[24:25], v[24:25], v[172:173]
	v_pk_mul_f32 v[30:31], v[30:31], v[170:171]
	v_pk_mul_f32 v[28:29], v[28:29], v[168:169]
	s_branch .LBB0_528
